# adds: sequence-DFT k-loop loads/LDS stores/pointer updates moved into its MFMA stream; out-projection A-base parameter loads hoisted out of the k-loop; diff-attention accumulator seed kept in a persis
# speedup vs baseline: 1.0155x; 1.0005x over previous
; template <bool SWAP, bool SSQ, class AF>
; DI void gemm_main(AF asrc, int m0, const u16* __restrict__ Bw, int ldb, int K, char* smem,
;                   f32x16 (&acc)[4][2], float ssq_eps, float (&rs)[4]) {
;     ...
;   for (int kt = 0; kt < nkt; ++kt) {
;     if (kt + 1 < nkt) gload(kt + 1);
;     __builtin_amdgcn_sched_barrier(0);
;     ...
;     __syncthreads();
;     if (kt + 1 < nkt) sstore();
;     __syncthreads();
;   }
.LBB0_38:
	s_cmp_lg_u32 s49, s15
	s_waitcnt lgkmcnt(0)
	s_barrier
	s_cbranch_scc0 .LBB0_43

; #define MFMA(a, b, c) __builtin_amdgcn_mfma_f32_32x32x16_bf16((a), (b), (c), 0, 0, 0)
; template <bool SWAP, bool SSQ, class AF>
; DI void gemm_main(AF asrc, int m0, const u16* __restrict__ Bw, int ldb, int K, char* smem,
;                   f32x16 (&acc)[4][2], float ssq_eps, float (&rs)[4]) {
;     ...
;   for (int kt = 0; kt < nkt; ++kt) {
;     if (kt + 1 < nkt) gload(kt + 1);
;     __builtin_amdgcn_sched_barrier(0);
;     {
;       bf16x8 ar[3], br[2][2];
;       ar[0] = *(const bf16x8*)(pA);
;       ar[1] = *(const bf16x8*)(pA + 32 * 144);
;       br[0][0] = *(const bf16x8*)(pB);
;       br[0][1] = *(const bf16x8*)(pB + 32 * 144);
;       __builtin_amdgcn_sched_group_barrier(0x100, 4, 0);
; #pragma unroll
;       for (int t = 0; t < 16; ++t) {
;         const int ks = t >> 2, mi = t & 3;
;         if (t + 2 < 16) {
;           ar[(t + 2) % 3] = *(const bf16x8*)(pA + ((t + 2) & 3) * (32 * 144) + ((t + 2) >> 2) * 32);
;           if (mi == 1 && ks + 1 < 4) {
;             br[(ks + 1) & 1][0] = *(const bf16x8*)(pB + (ks + 1) * 32);
;             br[(ks + 1) & 1][1] = *(const bf16x8*)(pB + 32 * 144 + (ks + 1) * 32);
;             __builtin_amdgcn_sched_group_barrier(0x100, 3, 0);
;           } else {
;             __builtin_amdgcn_sched_group_barrier(0x100, 1, 0);
;           }
;         }
;         acc[mi][0] = SWAP ? MFMA(br[ks & 1][0], ar[t % 3], acc[mi][0]) : MFMA(ar[t % 3], br[ks & 1][0], acc[mi][0]);
;         acc[mi][1] = SWAP ? MFMA(br[ks & 1][1], ar[t % 3], acc[mi][1]) : MFMA(ar[t % 3], br[ks & 1][1], acc[mi][1]);
;         __builtin_amdgcn_sched_group_barrier(0x008, 2, 0);
;         if (SSQ) {
;           u32x4 u = __builtin_bit_cast(u32x4, ar[t % 3]);
; #pragma unroll
;           for (int j = 0; j < 4; ++j) rs[mi] = dot2bf(u[j], rs[mi]);
;         }
;       }
;     }
;     __syncthreads();
;     if (kt + 1 < nkt) sstore();
;     __syncthreads();
.LBB0_41:
	ds_read_b128 v[180:183], v179 offset:36864
	ds_read_b128 v[194:197], v179 offset:41472
	ds_read_b128 v[186:189], v177
	ds_read_b128 v[190:193], v177 offset:4608
	ds_read_b128 v[218:221], v177 offset:9216
	s_andn2_b64 vcc, exec, s[44:45]
	s_waitcnt lgkmcnt(2)
	v_mfma_f32_32x32x16_bf16 v[112:127], v[180:183], v[186:189], v[112:127]
	v_mfma_f32_32x32x16_bf16 v[96:111], v[194:197], v[186:189], v[96:111]
	ds_read_b128 v[222:225], v179 offset:36896
	ds_read_b128 v[226:229], v179 offset:41504
	ds_read_b128 v[186:189], v177 offset:13824
	s_cbranch_vccnz .Ldft0_nl0
	v_lshl_add_u64 v[128:129], s[18:19], 0, v[184:185]
	v_lshl_add_u64 v[132:133], s[34:35], 0, v[184:185]
	global_load_dwordx4 v[128:131], v[128:129], off
	global_load_dwordx4 v[132:135], v[132:133], off
.Ldft0_nl0:
	s_add_u32 s18, s18, 0x80
	s_addc_u32 s19, s19, 0
	s_add_u32 s34, s34, 0x80
	s_addc_u32 s35, s35, 0
	s_waitcnt lgkmcnt(4)
	v_mfma_f32_32x32x16_bf16 v[80:95], v[180:183], v[190:193], v[80:95]
	v_mfma_f32_32x32x16_bf16 v[64:79], v[194:197], v[190:193], v[64:79]
	ds_read_b128 v[190:193], v177 offset:32
	s_cbranch_vccnz .Ldft0_nl1
	v_lshl_add_u64 v[136:137], s[20:21], 0, v[184:185]
	v_lshl_add_u64 v[140:141], s[22:23], 0, v[184:185]
	global_load_dwordx4 v[136:139], v[136:137], off
	global_load_dwordx4 v[140:143], v[140:141], off
.Ldft0_nl1:
	s_add_u32 s20, s20, 0x80
	s_addc_u32 s21, s21, 0
	s_add_u32 s22, s22, 0x80
	s_addc_u32 s23, s23, 0
	s_waitcnt lgkmcnt(4)
	v_mfma_f32_32x32x16_bf16 v[48:63], v[180:183], v[218:221], v[48:63]
	v_mfma_f32_32x32x16_bf16 v[32:47], v[194:197], v[218:221], v[32:47]
	ds_read_b128 v[218:221], v177 offset:4640
	s_cbranch_vccnz .Ldft0_nl2
	v_lshl_add_u64 v[144:145], s[24:25], 0, v[184:185]
	v_lshl_add_u64 v[148:149], s[26:27], 0, v[184:185]
	global_load_dwordx4 v[144:147], v[144:145], off
	global_load_dwordx4 v[148:151], v[148:149], off
.Ldft0_nl2:
	s_add_u32 s24, s24, 0x80
	s_addc_u32 s25, s25, 0
	s_add_u32 s26, s26, 0x80
	s_addc_u32 s27, s27, 0
	s_waitcnt lgkmcnt(2)
	v_mfma_f32_32x32x16_bf16 v[16:31], v[180:183], v[186:189], v[16:31]
	v_mfma_f32_32x32x16_bf16 v[0:15], v[194:197], v[186:189], v[0:15]
	ds_read_b128 v[180:183], v177 offset:9248
	s_cbranch_vccnz .Ldft0_nl3
	v_lshl_add_u64 v[152:153], s[28:29], 0, v[184:185]
	v_lshl_add_u64 v[156:157], s[30:31], 0, v[184:185]
	global_load_dwordx4 v[152:155], v[152:153], off
	global_load_dwordx4 v[156:159], v[156:157], off
.Ldft0_nl3:
	s_add_u32 s28, s28, 0x80
	s_addc_u32 s29, s29, 0
	s_add_u32 s30, s30, 0x80
	s_addc_u32 s31, s31, 0
	s_waitcnt lgkmcnt(2)
	v_mfma_f32_32x32x16_bf16 v[112:127], v[222:225], v[190:193], v[112:127]
	v_mfma_f32_32x32x16_bf16 v[96:111], v[226:229], v[190:193], v[96:111]
	ds_read_b128 v[190:193], v179 offset:36928
	ds_read_b128 v[194:197], v179 offset:41536
	ds_read_b128 v[186:189], v177 offset:13856
	s_cbranch_vccnz .Ldft0_nl4
	v_lshl_add_u64 v[160:161], s[36:37], 0, v[184:185]
	v_lshl_add_u64 v[164:165], s[42:43], 0, v[184:185]
	global_load_dwordx4 v[160:163], v[160:161], off
	global_load_dwordx4 v[164:167], v[164:165], off
.Ldft0_nl4:
	s_add_u32 s36, s36, 0x80
	s_addc_u32 s37, s37, 0
	s_add_u32 s42, s42, 0x80
	s_addc_u32 s43, s43, 0
	s_waitcnt lgkmcnt(4)
	v_mfma_f32_32x32x16_bf16 v[80:95], v[222:225], v[218:221], v[80:95]
	v_mfma_f32_32x32x16_bf16 v[64:79], v[226:229], v[218:221], v[64:79]
	ds_read_b128 v[218:221], v177 offset:64
	s_cbranch_vccnz .Ldft0_nl5
	v_lshl_add_u64 v[168:169], s[38:39], 0, v[184:185]
	v_lshl_add_u64 v[172:173], s[40:41], 0, v[184:185]
	global_load_dwordx4 v[168:171], v[168:169], off
	global_load_dwordx4 v[172:175], v[172:173], off
.Ldft0_nl5:
	s_add_u32 s38, s38, 0x80
	s_addc_u32 s39, s39, 0
	s_add_u32 s40, s40, 0x80
	s_addc_u32 s41, s41, 0
	s_waitcnt lgkmcnt(4)
	v_mfma_f32_32x32x16_bf16 v[48:63], v[222:225], v[180:183], v[48:63]
	v_mfma_f32_32x32x16_bf16 v[32:47], v[226:229], v[180:183], v[32:47]
	ds_read_b128 v[180:183], v177 offset:4672
	s_waitcnt lgkmcnt(2)
	v_mfma_f32_32x32x16_bf16 v[16:31], v[222:225], v[186:189], v[16:31]
	v_mfma_f32_32x32x16_bf16 v[0:15], v[226:229], v[186:189], v[0:15]
	ds_read_b128 v[186:189], v177 offset:9280
	s_waitcnt lgkmcnt(2)
	v_mfma_f32_32x32x16_bf16 v[112:127], v[190:193], v[218:221], v[112:127]
	v_mfma_f32_32x32x16_bf16 v[96:111], v[194:197], v[218:221], v[96:111]
	ds_read_b128 v[222:225], v179 offset:36960
	ds_read_b128 v[226:229], v179 offset:41568
	ds_read_b128 v[218:221], v177 offset:13888
	s_waitcnt lgkmcnt(4)
	v_mfma_f32_32x32x16_bf16 v[80:95], v[190:193], v[180:183], v[80:95]
	v_mfma_f32_32x32x16_bf16 v[64:79], v[194:197], v[180:183], v[64:79]
	ds_read_b128 v[180:183], v177 offset:96
	s_waitcnt lgkmcnt(4)
	v_mfma_f32_32x32x16_bf16 v[48:63], v[190:193], v[186:189], v[48:63]
	v_mfma_f32_32x32x16_bf16 v[32:47], v[194:197], v[186:189], v[32:47]
	ds_read_b128 v[186:189], v177 offset:4704
	s_waitcnt lgkmcnt(2)
	v_mfma_f32_32x32x16_bf16 v[16:31], v[190:193], v[218:221], v[16:31]
	v_mfma_f32_32x32x16_bf16 v[0:15], v[194:197], v[218:221], v[0:15]
	ds_read_b128 v[190:193], v177 offset:9312
	s_waitcnt lgkmcnt(2)
	v_mfma_f32_32x32x16_bf16 v[112:127], v[222:225], v[180:183], v[112:127]
	v_mfma_f32_32x32x16_bf16 v[96:111], v[226:229], v[180:183], v[96:111]
	ds_read_b128 v[180:183], v177 offset:13920
	s_waitcnt lgkmcnt(0)
	s_barrier
	s_cbranch_vccnz .Ldft0_last
	v_mfma_f32_32x32x16_bf16 v[80:95], v[222:225], v[186:189], v[80:95]
	s_waitcnt vmcnt(11)
	ds_write_b128 v176, v[128:131]
	s_waitcnt vmcnt(10)
	ds_write_b128 v176, v[132:135] offset:4608
	v_mfma_f32_32x32x16_bf16 v[64:79], v[226:229], v[186:189], v[64:79]
	s_waitcnt vmcnt(9)
	ds_write_b128 v176, v[136:139] offset:9216
	s_waitcnt vmcnt(8)
	ds_write_b128 v176, v[140:143] offset:13824
	v_mfma_f32_32x32x16_bf16 v[48:63], v[222:225], v[190:193], v[48:63]
	s_waitcnt vmcnt(7)
	ds_write_b128 v176, v[144:147] offset:18432
	s_waitcnt vmcnt(6)
	ds_write_b128 v176, v[148:151] offset:23040
	v_mfma_f32_32x32x16_bf16 v[32:47], v[226:229], v[190:193], v[32:47]
	s_waitcnt vmcnt(5)
	ds_write_b128 v176, v[152:155] offset:27648
	s_waitcnt vmcnt(4)
	ds_write_b128 v176, v[156:159] offset:32256
	v_mfma_f32_32x32x16_bf16 v[16:31], v[222:225], v[180:183], v[16:31]
	s_waitcnt vmcnt(3)
	ds_write_b128 v176, v[160:163] offset:36864
	s_waitcnt vmcnt(2)
	ds_write_b128 v176, v[164:167] offset:41472
	v_mfma_f32_32x32x16_bf16 v[0:15], v[226:229], v[180:183], v[0:15]
	s_waitcnt vmcnt(1)
	ds_write_b128 v176, v[168:171] offset:46080
	s_waitcnt vmcnt(0)
	ds_write_b128 v176, v[172:175] offset:50688
	s_branch .LBB0_38
.Ldft0_last:
	v_mfma_f32_32x32x16_bf16 v[80:95], v[222:225], v[186:189], v[80:95]
	v_mfma_f32_32x32x16_bf16 v[64:79], v[226:229], v[186:189], v[64:79]
	v_mfma_f32_32x32x16_bf16 v[48:63], v[222:225], v[190:193], v[48:63]
	v_mfma_f32_32x32x16_bf16 v[32:47], v[226:229], v[190:193], v[32:47]
	v_mfma_f32_32x32x16_bf16 v[16:31], v[222:225], v[180:183], v[16:31]
	v_mfma_f32_32x32x16_bf16 v[0:15], v[226:229], v[180:183], v[0:15]
	s_branch .LBB0_38

; template <bool SWAP, bool SSQ, class AF>
; DI void gemm_main(AF asrc, int m0, const u16* __restrict__ Bw, int ldb, int K, char* smem,
;                   f32x16 (&acc)[4][2], float ssq_eps, float (&rs)[4]) {
;     ...
;   for (int kt = 0; kt < nkt; ++kt) {
;     if (kt + 1 < nkt) gload(kt + 1);
;     __builtin_amdgcn_sched_barrier(0);
;     ...
;     __syncthreads();
;     if (kt + 1 < nkt) sstore();
;     __syncthreads();
;   }
.LBB0_62:
	s_cmp_lg_u32 s50, s15
	s_waitcnt lgkmcnt(0)
	s_barrier
	s_cbranch_scc0 .LBB0_67

; #define MFMA(a, b, c) __builtin_amdgcn_mfma_f32_32x32x16_bf16((a), (b), (c), 0, 0, 0)
; DI void softmax_pv(f32x16 (&sa)[2], f32x16 (&O)[4], float& m, float& l, const char* sV, int lr, int lh, bool first) {
;   float t0 = fmaxf(fmaxf(sa[0][0], sa[0][1]), sa[0][2]);
;   float t1 = fmaxf(fmaxf(sa[1][0], sa[1][1]), sa[1][2]);
; #pragma unroll
;   for (int i = 3; i < 15; i += 2) {
;     t0 = fmaxf(fmaxf(t0, sa[0][i]), sa[0][i + 1]);
;     t1 = fmaxf(fmaxf(t1, sa[1][i]), sa[1][i + 1]);
;   }
;   float tmax = fmaxf(fmaxf(t0, t1), fmaxf(sa[0][15], sa[1][15]));
;   tmax = fmaxf(tmax, __shfl_xor(tmax, 32, 64));
;   if (first || __any(tmax > SM_THR)) {
;     asm volatile("; rescale" ::: "memory");
;     const float delta = first ? tmax : fmaxf(tmax, 0.f);
;     const float alpha = __builtin_amdgcn_exp2f(-delta);
;     m += delta;
;     l *= alpha;
; #pragma unroll
;     for (int d = 0; d < 4; ++d)
; #pragma unroll
;       for (int i = 0; i < 16; ++i) O[d][i] *= alpha;
; #pragma unroll
;     for (int i = 0; i < 16; ++i) { sa[0][i] -= delta; sa[1][i] -= delta; }
;   }
;   float rsum0 = 0.f, rsum1 = 0.f;
; #pragma unroll
;   for (int i = 0; i < 16; ++i) {
;     float p0 = __builtin_amdgcn_exp2f(sa[0][i]);
;     float p1 = __builtin_amdgcn_exp2f(sa[1][i]);
;     sa[0][i] = p0;
;     sa[1][i] = p1;
;     rsum0 += p0;
;     rsum1 += p1;
;   }
;   l += rsum0 + rsum1;
;   bf16x8 pf[4];
; #pragma unroll
;   for (int g4 = 0; g4 < 4; ++g4) {
;     const int kb = g4 >> 1, s2 = g4 & 1;
;     u32x4 pp;
; #pragma unroll
;     for (int j = 0; j < 4; ++j) pp[j] = pk2(sa[kb][8 * s2 + 2 * j], sa[kb][8 * s2 + 2 * j + 1]);
;     pf[g4] = __builtin_bit_cast(bf16x8, pp);
;   }
;   const char* vrd = sV + lr * 144 + lh * 16;
;   bf16x8 vfr[4];
; #pragma unroll
;   for (int t = 0; t < 3; ++t) vfr[t] = *(const bf16x8*)(vrd + (t & 3) * (32 * 144) + (t >> 2) * 32);
;   __builtin_amdgcn_sched_group_barrier(0x100, 3, 0);
; #pragma unroll
;   for (int t = 0; t < 16; ++t) {
;     if (t + 3 < 16) {
;       vfr[(t + 3) & 3] = *(const bf16x8*)(vrd + ((t + 3) & 3) * (32 * 144) + ((t + 3) >> 2) * 32);
;       __builtin_amdgcn_sched_group_barrier(0x100, 1, 0);
;     }
;     O[t & 3] = MFMA(vfr[t & 3], pf[t >> 2], O[t & 3]);
;     __builtin_amdgcn_sched_group_barrier(0x008, 1, 0);
;   }
; }
.LBB0_119:
	v_mul_u32_u24_e32 v32, 0x110, v154
	v_lshlrev_b32_e32 v33, 7, v154
	v_sub_u32_e32 v50, v32, v33
	v_max3_f32 v32, v0, v1, v2
	v_max3_f32 v33, v16, v17, v18
	v_max3_f32 v32, v32, v3, v4
	v_max3_f32 v33, v33, v19, v20
	v_max3_f32 v32, v32, v5, v6
	v_max3_f32 v33, v33, v21, v22
	v_max3_f32 v32, v32, v7, v8
	v_max3_f32 v33, v33, v23, v24
	v_max3_f32 v32, v32, v9, v10
	v_max3_f32 v33, v33, v25, v26
	v_max3_f32 v32, v32, v11, v12
	v_max3_f32 v33, v33, v27, v28
	v_max_f32_e32 v34, v31, v31
	v_max_f32_e32 v35, v15, v15
	v_max3_f32 v32, v32, v13, v14
	v_max3_f32 v33, v33, v29, v30
	v_max_f32_e32 v34, v35, v34
	v_mbcnt_hi_u32_b32 v162, -1, v211
	v_max3_f32 v32, v32, v33, v34
	v_and_b32_e32 v33, 64, v162
	v_xor_b32_e32 v160, 32, v162
	v_add_u32_e32 v161, 64, v33
	v_cmp_lt_i32_e32 vcc, v160, v161
	v_add_u32_e32 v165, v50, v144
	ds_read_b128 v[84:87], v165 offset:26624
	v_cndmask_b32_e32 v33, v162, v160, vcc
	v_lshlrev_b32_e32 v164, 2, v33
	ds_bpermute_b32 v33, v164, v32
	s_and_b64 vcc, exec, s[8:9]
	s_waitcnt lgkmcnt(0)
	v_max_f32_e32 v33, v33, v33
	v_max_f32_e32 v82, v32, v33
	v_sub_f32_e32 v16, v16, v82
	v_sub_f32_e32 v32, v17, v82
	v_sub_f32_e32 v17, v0, v82
	v_sub_f32_e32 v33, v18, v82
	v_sub_f32_e32 v18, v1, v82
	v_exp_f32_e32 v17, v17
	v_exp_f32_e32 v16, v16
	v_sub_f32_e32 v34, v19, v82
	v_sub_f32_e32 v35, v20, v82
	v_sub_f32_e32 v20, v2, v82
	v_exp_f32_e32 v19, v18
	v_exp_f32_e32 v18, v32
	v_sub_f32_e32 v36, v21, v82
	v_sub_f32_e32 v37, v22, v82
	v_sub_f32_e32 v22, v3, v82
	v_exp_f32_e32 v21, v20
	v_exp_f32_e32 v20, v33
	v_sub_f32_e32 v38, v23, v82
	v_sub_f32_e32 v41, v26, v82
	v_sub_f32_e32 v26, v4, v82
	v_exp_f32_e32 v23, v22
	v_exp_f32_e32 v22, v34
	v_sub_f32_e32 v39, v24, v82
	v_sub_f32_e32 v40, v25, v82
	v_sub_f32_e32 v42, v27, v82
	v_sub_f32_e32 v44, v28, v82
	v_sub_f32_e32 v28, v5, v82
	v_pk_add_f32 v[24:25], v[16:17], 0 op_sel_hi:[1,0]
	v_exp_f32_e32 v27, v26
	v_exp_f32_e32 v26, v35
	v_sub_f32_e32 v46, v29, v82
	v_sub_f32_e32 v48, v30, v82
	v_sub_f32_e32 v30, v6, v82
	v_pk_add_f32 v[24:25], v[18:19], v[24:25]
	v_exp_f32_e32 v29, v28
	v_exp_f32_e32 v28, v36
	v_sub_f32_e32 v51, v31, v82
	v_sub_f32_e32 v43, v7, v82
	v_pk_add_f32 v[24:25], v[20:21], v[24:25]
	v_exp_f32_e32 v31, v30
	v_exp_f32_e32 v30, v37
	v_sub_f32_e32 v45, v8, v82
	v_pk_add_f32 v[24:25], v[22:23], v[24:25]
	v_exp_f32_e32 v33, v43
	v_exp_f32_e32 v32, v38
	v_sub_f32_e32 v47, v9, v82
	v_exp_f32_e32 v35, v45
	v_exp_f32_e32 v34, v39
	v_pk_add_f32 v[24:25], v[26:27], v[24:25]
	v_sub_f32_e32 v49, v10, v82
	v_exp_f32_e32 v37, v47
	v_exp_f32_e32 v36, v40
	v_pk_add_f32 v[24:25], v[28:29], v[24:25]
	v_sub_f32_e32 v52, v11, v82
	v_exp_f32_e32 v39, v49
	v_exp_f32_e32 v38, v41
	v_pk_add_f32 v[24:25], v[30:31], v[24:25]
	v_sub_f32_e32 v53, v12, v82
	v_exp_f32_e32 v41, v52
	v_exp_f32_e32 v40, v42
	v_pk_add_f32 v[24:25], v[32:33], v[24:25]
	v_sub_f32_e32 v54, v13, v82
	v_exp_f32_e32 v43, v53
	v_exp_f32_e32 v42, v44
	v_pk_add_f32 v[24:25], v[34:35], v[24:25]
	v_cvt_pk_bf16_f32 v76, v17, v19
	v_cvt_pk_bf16_f32 v77, v21, v23
	v_cvt_pk_bf16_f32 v68, v16, v18
	v_cvt_pk_bf16_f32 v69, v20, v22
	ds_read_b128 v[16:19], v165 offset:17408
	ds_read_b128 v[20:23], v165 offset:22016
	ds_read_b128 v[88:91], v165 offset:31232
	v_sub_f32_e32 v55, v14, v82
	v_exp_f32_e32 v45, v54
	v_exp_f32_e32 v44, v46
	v_pk_add_f32 v[24:25], v[36:37], v[24:25]
	v_sub_f32_e32 v56, v15, v82
	v_exp_f32_e32 v47, v55
	v_exp_f32_e32 v46, v48
	v_pk_add_f32 v[24:25], v[38:39], v[24:25]
	v_exp_f32_e64 v57, -v82
	v_exp_f32_e32 v49, v56
	v_exp_f32_e32 v48, v51
	v_pk_add_f32 v[24:25], v[40:41], v[24:25]
	v_mul_f32_e32 v0, 0, v57
	v_pk_add_f32 v[24:25], v[42:43], v[24:25]
	v_mov_b32_e32 v1, v0
	v_pk_add_f32 v[24:25], v[44:45], v[24:25]
	v_mov_b32_e32 v2, v0
	v_pk_add_f32 v[24:25], v[46:47], v[24:25]
	v_mov_b32_e32 v3, v0
	v_pk_add_f32 v[24:25], v[48:49], v[24:25]
	v_mov_b32_e32 v4, v0
	v_mov_b32_e32 v5, v0
	v_mov_b32_e32 v6, v0
	v_mov_b32_e32 v7, v0
	v_mov_b32_e32 v8, v0
	v_mov_b32_e32 v9, v0
	v_mov_b32_e32 v10, v0
	v_mov_b32_e32 v11, v0
	v_mov_b32_e32 v12, v0
	v_mov_b32_e32 v13, v0
	v_mov_b32_e32 v14, v0
	v_mov_b32_e32 v15, v0
	v_add_f32_e32 v163, v24, v25
	v_cvt_pk_bf16_f32 v78, v27, v29
	v_cvt_pk_bf16_f32 v79, v31, v33
	v_fmac_f32_e32 v163, 0, v57
	v_cvt_pk_bf16_f32 v72, v35, v37
	v_cvt_pk_bf16_f32 v73, v39, v41
	v_cvt_pk_bf16_f32 v74, v43, v45
	v_cvt_pk_bf16_f32 v75, v47, v49
	v_cvt_pk_bf16_f32 v70, v26, v28
	v_cvt_pk_bf16_f32 v71, v30, v32
	v_cvt_pk_bf16_f32 v64, v34, v36
	v_cvt_pk_bf16_f32 v65, v38, v40
	v_cvt_pk_bf16_f32 v66, v42, v44
	v_cvt_pk_bf16_f32 v67, v46, v48
	s_waitcnt lgkmcnt(2)
	v_mfma_f32_32x32x16_bf16 v[48:63], v[16:19], v[76:79], v[0:15]
	ds_read_b128 v[92:95], v165 offset:17440
	s_waitcnt lgkmcnt(2)
	v_mfma_f32_32x32x16_bf16 v[32:47], v[20:23], v[76:79], v[0:15]
	ds_read_b128 v[166:169], v165 offset:22048
	v_mfma_f32_32x32x16_bf16 v[16:31], v[84:87], v[76:79], v[0:15]
	ds_read_b128 v[84:87], v165 offset:26656
	s_waitcnt lgkmcnt(3)
	v_mfma_f32_32x32x16_bf16 v[0:15], v[88:91], v[76:79], v[0:15]
	ds_read_b128 v[76:79], v165 offset:31264
	s_waitcnt lgkmcnt(3)
	v_mfma_f32_32x32x16_bf16 v[48:63], v[92:95], v[72:75], v[48:63]
	ds_read_b128 v[88:91], v165 offset:17472
	s_waitcnt lgkmcnt(3)
	v_mfma_f32_32x32x16_bf16 v[32:47], v[166:169], v[72:75], v[32:47]
	ds_read_b128 v[92:95], v165 offset:22080
	s_waitcnt lgkmcnt(3)
	v_mfma_f32_32x32x16_bf16 v[16:31], v[84:87], v[72:75], v[16:31]
	ds_read_b128 v[84:87], v165 offset:26688
	s_waitcnt lgkmcnt(3)
	v_mfma_f32_32x32x16_bf16 v[0:15], v[76:79], v[72:75], v[0:15]
	ds_read_b128 v[72:75], v165 offset:31296
	s_waitcnt lgkmcnt(3)
	v_mfma_f32_32x32x16_bf16 v[48:63], v[88:91], v[68:71], v[48:63]
	ds_read_b128 v[76:79], v165 offset:17504
	s_waitcnt lgkmcnt(3)
	v_mfma_f32_32x32x16_bf16 v[32:47], v[92:95], v[68:71], v[32:47]
	ds_read_b128 v[88:91], v165 offset:22112
	s_waitcnt lgkmcnt(3)
	v_mfma_f32_32x32x16_bf16 v[16:31], v[84:87], v[68:71], v[16:31]
	ds_read_b128 v[84:87], v165 offset:26720
	s_waitcnt lgkmcnt(3)
	v_mfma_f32_32x32x16_bf16 v[0:15], v[72:75], v[68:71], v[0:15]
	ds_read_b128 v[68:71], v165 offset:31328
	s_waitcnt lgkmcnt(0)
	s_barrier
; #define MFMA(a, b, c) __builtin_amdgcn_mfma_f32_32x32x16_bf16((a), (b), (c), 0, 0, 0)
; DI void softmax_pv(f32x16 (&sa)[2], f32x16 (&O)[4], float& m, float& l, const char* sV, int lr, int lh, bool first) {
;     ...
;   for (int t = 0; t < 16; ++t) {
;     if (t + 3 < 16) {
;       vfr[(t + 3) & 3] = *(const bf16x8*)(vrd + ((t + 3) & 3) * (32 * 144) + ((t + 3) >> 2) * 32);
;       __builtin_amdgcn_sched_group_barrier(0x100, 1, 0);
;     }
;     O[t & 3] = MFMA(vfr[t & 3], pf[t >> 2], O[t & 3]);
;     __builtin_amdgcn_sched_group_barrier(0x008, 1, 0);
;   }
; }
; DI void diff_item(const Params& p, const GroupP& g, int l_layer, int item, char* smem, bool dry) {
;     ...
;     if (more) { storeK(); load_vtile(rv, vbase, Lp, (kt + 1) * 64, voffV); }
;     __builtin_amdgcn_sched_barrier(0);
;     softmax_pv(sa, O, m, l, sV, lr, lh, kt == 0);
;     __syncthreads();
;     if (more) store_vtile(rv, sV_st);
	v_mfma_f32_32x32x16_bf16 v[48:63], v[76:79], v[64:67], v[48:63]
	v_mfma_f32_32x32x16_bf16 v[32:47], v[88:91], v[64:67], v[32:47]
	v_mfma_f32_32x32x16_bf16 v[16:31], v[84:87], v[64:67], v[16:31]
	v_mfma_f32_32x32x16_bf16 v[0:15], v[68:71], v[64:67], v[0:15]
	s_cbranch_vccnz .LBB0_134
	s_lshl_b32 s4, s48, 6
	v_add_u32_e32 v64, v80, v81
	s_or_b32 s5, s4, s47
	v_add_u32_e32 v167, 0x4000, v64
	v_add_u32_e32 v168, 0x5000, v64
	v_add_u32_e32 v169, 0x6800, v64
	v_add_u32_e32 v170, 0x7800, v64
	v_add_u32_e32 v64, s5, v154
	v_readlane_b32 s5, v255, 43
	s_mul_i32 s5, s5, s49
	v_readlane_b32 s8, v255, 44
	v_sub_u32_e32 v64, s5, v64
	s_sub_i32 s5, s5, s47
	s_sub_i32 s4, s5, s4
	s_add_u32 s5, s42, s94
	s_addc_u32 s9, s43, 0
	s_add_u32 s8, s8, s5
	v_readlane_b32 s5, v255, 45
	s_addc_u32 s9, s5, s9
	v_add_f32_e32 v166, 0, v82
	v_add_u32_e32 v171, v156, v64
	v_lshl_add_u64 v[152:153], s[8:9], 0, v[184:185]
	s_mov_b32 s5, 0
	s_movk_i32 s94, 0x100
	s_mov_b32 s42, 0
	v_readlane_b32 s43, v255, 32
	s_waitcnt vmcnt(3)
	ds_write2_b64 v167, v[120:121], v[122:123] offset0:128 offset1:130
	s_waitcnt vmcnt(2)
	ds_write2_b64 v168, v[124:125], v[126:127] offset0:192 offset1:194
	s_waitcnt vmcnt(1)
	ds_write2_b64 v169, v[128:129], v[130:131] offset1:2
	s_waitcnt vmcnt(0)
	ds_write2_b64 v170, v[132:133], v[134:135] offset0:64 offset1:66
	v_mov_b32_e32 v218, 0x7fc00000
	s_branch .LBB0_122

; #define MFMA(a, b, c) __builtin_amdgcn_mfma_f32_32x32x16_bf16((a), (b), (c), 0, 0, 0)
; DI void diff_item(const Params& p, const GroupP& g, int l_layer, int item, char* smem, bool dry) {
;     ...
;     const int key0 = kt * 64;
;     const int relmin = key0 - (qw0 + 31), relmax = key0 + 63 - qw0;
;     const bool farp = relmin >= 128, farn = relmax <= -128;
;     const float binit = (farp ? bpos : (farn ? bneg : 0.f)) - m;
;     f32x16 sa[2];
; #pragma unroll
;     for (int i = 0; i < 16; ++i) { sa[0][i] = binit; sa[1][i] = binit; }
;     {
;       const char* krd = sK + lr * 272 + map * 128 + lh * 16;
;       bf16x8 kf[4][2];
; #pragma unroll
;       for (int ks = 0; ks < 4; ++ks) {
;         kf[ks][0] = *(const bf16x8*)(krd + ks * 32);
;         kf[ks][1] = *(const bf16x8*)(krd + 32 * 272 + ks * 32);
;       }
; #pragma unroll
;       for (int ks = 0; ks < 4; ++ks) {
;         sa[0] = MFMA(kf[ks][0], qf[ks], sa[0]);
;         sa[1] = MFMA(kf[ks][1], qf[ks], sa[1]);
;       }
.LBB0_124:
	s_add_i32 s10, s4, s5
	ds_read_b128 v[172:175], v159
	ds_read_b128 v[176:179], v159 offset:8704
	ds_read_b128 v[180:183], v159 offset:32
	ds_read_b128 v[188:191], v159 offset:8736
	s_add_i32 s8, s10, 33
	s_add_i32 s9, s10, 0x7f
	s_cmpk_gt_i32 s8, 0x7f
	s_cselect_b64 vcc, -1, 0
	s_cmpk_lt_i32 s9, 0xff81
	s_cselect_b64 s[8:9], -1, 0
	v_cndmask_b32_e64 v234, 0, v157, s[8:9]
	v_cndmask_b32_e32 v234, v234, v158, vcc
	v_sub_f32_e32 v234, v234, v166
	v_cmp_neq_f32_e32 vcc, v234, v218
	s_cbranch_vccz .Ldsd0_keep
	v_mov_b32_e32 v218, v234
	v_mov_b32_e32 v219, v234
	v_mov_b32_e32 v220, v234
	v_mov_b32_e32 v221, v234
	v_mov_b32_e32 v222, v234
	v_mov_b32_e32 v223, v234
	v_mov_b32_e32 v224, v234
	v_mov_b32_e32 v225, v234
	v_mov_b32_e32 v226, v234
	v_mov_b32_e32 v227, v234
	v_mov_b32_e32 v228, v234
	v_mov_b32_e32 v229, v234
	v_mov_b32_e32 v230, v234
	v_mov_b32_e32 v231, v234
	v_mov_b32_e32 v232, v234
	v_mov_b32_e32 v233, v234
.Ldsd0_keep:
	s_addk_i32 s10, 0xffa1
	s_waitcnt lgkmcnt(3)
	v_mfma_f32_32x32x16_bf16 v[80:95], v[172:175], v[96:99], v[218:233]
	s_waitcnt lgkmcnt(2)
	v_mfma_f32_32x32x16_bf16 v[64:79], v[176:179], v[96:99], v[218:233]
	s_add_i32 s100, s42, 2
	s_cmp_ge_i32 s100, s85
	s_cbranch_scc1 .Ldqk0_nokld
	s_mov_b64 s[100:101], 0x4000
	global_load_dwordx4 v[116:119], v[152:153], off
	v_lshl_add_u64 v[112:113], v[152:153], 0, s[100:101]
	v_lshl_add_u64 v[136:137], v[112:113], 0, s[100:101]
	v_lshl_add_u64 v[140:141], v[136:137], 0, s[100:101]
	global_load_dwordx4 v[112:115], v[112:113], off
	global_load_dwordx4 v[136:139], v[136:137], off
	global_load_dwordx4 v[140:143], v[140:141], off

; #define MFMA(a, b, c) __builtin_amdgcn_mfma_f32_32x32x16_bf16((a), (b), (c), 0, 0, 0)
; DI void softmax_pv(f32x16 (&sa)[2], f32x16 (&O)[4], float& m, float& l, const char* sV, int lr, int lh, bool first) {
;   float t0 = fmaxf(fmaxf(sa[0][0], sa[0][1]), sa[0][2]);
;   float t1 = fmaxf(fmaxf(sa[1][0], sa[1][1]), sa[1][2]);
; #pragma unroll
;   for (int i = 3; i < 15; i += 2) {
;     t0 = fmaxf(fmaxf(t0, sa[0][i]), sa[0][i + 1]);
;     t1 = fmaxf(fmaxf(t1, sa[1][i]), sa[1][i + 1]);
;   }
;   float tmax = fmaxf(fmaxf(t0, t1), fmaxf(sa[0][15], sa[1][15]));
;   tmax = fmaxf(tmax, __shfl_xor(tmax, 32, 64));
;   if (first || __any(tmax > SM_THR)) {
;     asm volatile("; rescale" ::: "memory");
;     const float delta = first ? tmax : fmaxf(tmax, 0.f);
;     const float alpha = __builtin_amdgcn_exp2f(-delta);
;     m += delta;
;     l *= alpha;
; #pragma unroll
;     for (int d = 0; d < 4; ++d)
; #pragma unroll
;       for (int i = 0; i < 16; ++i) O[d][i] *= alpha;
; #pragma unroll
;     for (int i = 0; i < 16; ++i) { sa[0][i] -= delta; sa[1][i] -= delta; }
;   }
;   float rsum0 = 0.f, rsum1 = 0.f;
; #pragma unroll
;   for (int i = 0; i < 16; ++i) {
;     float p0 = __builtin_amdgcn_exp2f(sa[0][i]);
;     float p1 = __builtin_amdgcn_exp2f(sa[1][i]);
;     sa[0][i] = p0;
;     sa[1][i] = p1;
;     rsum0 += p0;
;     rsum1 += p1;
;   }
;   l += rsum0 + rsum1;
;   bf16x8 pf[4];
; #pragma unroll
;   for (int g4 = 0; g4 < 4; ++g4) {
;     const int kb = g4 >> 1, s2 = g4 & 1;
;     u32x4 pp;
; #pragma unroll
;     for (int j = 0; j < 4; ++j) pp[j] = pk2(sa[kb][8 * s2 + 2 * j], sa[kb][8 * s2 + 2 * j + 1]);
;     pf[g4] = __builtin_bit_cast(bf16x8, pp);
;   }
;   const char* vrd = sV + lr * 144 + lh * 16;
;   bf16x8 vfr[4];
; #pragma unroll
;   for (int t = 0; t < 3; ++t) vfr[t] = *(const bf16x8*)(vrd + (t & 3) * (32 * 144) + (t >> 2) * 32);
;   __builtin_amdgcn_sched_group_barrier(0x100, 3, 0);
; #pragma unroll
;   for (int t = 0; t < 16; ++t) {
;     if (t + 3 < 16) {
;       vfr[(t + 3) & 3] = *(const bf16x8*)(vrd + ((t + 3) & 3) * (32 * 144) + ((t + 3) >> 2) * 32);
;       __builtin_amdgcn_sched_group_barrier(0x100, 1, 0);
;     }
;     O[t & 3] = MFMA(vfr[t & 3], pf[t >> 2], O[t & 3]);
;     __builtin_amdgcn_sched_group_barrier(0x008, 1, 0);
;   }
; }
.LBB0_191:
	v_mul_u32_u24_e32 v32, 0x110, v154
	v_lshlrev_b32_e32 v33, 7, v154
	v_sub_u32_e32 v50, v32, v33
	v_max3_f32 v32, v0, v1, v2
	v_max3_f32 v33, v16, v17, v18
	v_max3_f32 v32, v32, v3, v4
	v_max3_f32 v33, v33, v19, v20
	v_max3_f32 v32, v32, v5, v6
	v_max3_f32 v33, v33, v21, v22
	v_max3_f32 v32, v32, v7, v8
	v_max3_f32 v33, v33, v23, v24
	v_max3_f32 v32, v32, v9, v10
	v_max3_f32 v33, v33, v25, v26
	v_max3_f32 v32, v32, v11, v12
	v_max3_f32 v33, v33, v27, v28
	v_max_f32_e32 v34, v31, v31
	v_max_f32_e32 v35, v15, v15
	v_max3_f32 v32, v32, v13, v14
	v_max3_f32 v33, v33, v29, v30
	v_max_f32_e32 v34, v35, v34
	v_mbcnt_hi_u32_b32 v160, -1, v211
	v_max3_f32 v32, v32, v33, v34
	v_and_b32_e32 v33, 64, v160
	v_xor_b32_e32 v161, 32, v160
	v_add_u32_e32 v162, 64, v33
	v_cmp_lt_i32_e32 vcc, v161, v162
	v_add_u32_e32 v165, v50, v144
	ds_read_b128 v[84:87], v165 offset:26624
	v_cndmask_b32_e32 v33, v160, v161, vcc
	v_lshlrev_b32_e32 v164, 2, v33
	ds_bpermute_b32 v33, v164, v32
	s_and_b64 vcc, exec, s[8:9]
	s_waitcnt lgkmcnt(0)
	v_max_f32_e32 v33, v33, v33
	v_max_f32_e32 v82, v32, v33
	v_sub_f32_e32 v16, v16, v82
	v_sub_f32_e32 v32, v17, v82
	v_sub_f32_e32 v17, v0, v82
	v_sub_f32_e32 v33, v18, v82
	v_sub_f32_e32 v18, v1, v82
	v_exp_f32_e32 v17, v17
	v_exp_f32_e32 v16, v16
	v_sub_f32_e32 v34, v19, v82
	v_sub_f32_e32 v35, v20, v82
	v_sub_f32_e32 v20, v2, v82
	v_exp_f32_e32 v19, v18
	v_exp_f32_e32 v18, v32
	v_sub_f32_e32 v36, v21, v82
	v_sub_f32_e32 v37, v22, v82
	v_sub_f32_e32 v22, v3, v82
	v_exp_f32_e32 v21, v20
	v_exp_f32_e32 v20, v33
	v_sub_f32_e32 v38, v23, v82
	v_sub_f32_e32 v41, v26, v82
	v_sub_f32_e32 v26, v4, v82
	v_exp_f32_e32 v23, v22
	v_exp_f32_e32 v22, v34
	v_sub_f32_e32 v39, v24, v82
	v_sub_f32_e32 v40, v25, v82
	v_sub_f32_e32 v42, v27, v82
	v_sub_f32_e32 v44, v28, v82
	v_sub_f32_e32 v28, v5, v82
	v_pk_add_f32 v[24:25], v[16:17], 0 op_sel_hi:[1,0]
	v_exp_f32_e32 v27, v26
	v_exp_f32_e32 v26, v35
	v_sub_f32_e32 v46, v29, v82
	v_sub_f32_e32 v48, v30, v82
	v_sub_f32_e32 v30, v6, v82
	v_pk_add_f32 v[24:25], v[18:19], v[24:25]
	v_exp_f32_e32 v29, v28
	v_exp_f32_e32 v28, v36
	v_sub_f32_e32 v51, v31, v82
	v_sub_f32_e32 v43, v7, v82
	v_pk_add_f32 v[24:25], v[20:21], v[24:25]
	v_exp_f32_e32 v31, v30
	v_exp_f32_e32 v30, v37
	v_sub_f32_e32 v45, v8, v82
	v_pk_add_f32 v[24:25], v[22:23], v[24:25]
	v_exp_f32_e32 v33, v43
	v_exp_f32_e32 v32, v38
	v_sub_f32_e32 v47, v9, v82
	v_exp_f32_e32 v35, v45
	v_exp_f32_e32 v34, v39
	v_pk_add_f32 v[24:25], v[26:27], v[24:25]
	v_sub_f32_e32 v49, v10, v82
	v_exp_f32_e32 v37, v47
	v_exp_f32_e32 v36, v40
	v_pk_add_f32 v[24:25], v[28:29], v[24:25]
	v_sub_f32_e32 v52, v11, v82
	v_exp_f32_e32 v39, v49
	v_exp_f32_e32 v38, v41
	v_pk_add_f32 v[24:25], v[30:31], v[24:25]
	v_sub_f32_e32 v53, v12, v82
	v_exp_f32_e32 v41, v52
	v_exp_f32_e32 v40, v42
	v_pk_add_f32 v[24:25], v[32:33], v[24:25]
	v_sub_f32_e32 v54, v13, v82
	v_exp_f32_e32 v43, v53
	v_exp_f32_e32 v42, v44
	v_pk_add_f32 v[24:25], v[34:35], v[24:25]
	v_cvt_pk_bf16_f32 v76, v17, v19
	v_cvt_pk_bf16_f32 v77, v21, v23
	v_cvt_pk_bf16_f32 v68, v16, v18
	v_cvt_pk_bf16_f32 v69, v20, v22
	ds_read_b128 v[16:19], v165 offset:17408
	ds_read_b128 v[20:23], v165 offset:22016
	ds_read_b128 v[88:91], v165 offset:31232
	v_sub_f32_e32 v55, v14, v82
	v_exp_f32_e32 v45, v54
	v_exp_f32_e32 v44, v46
	v_pk_add_f32 v[24:25], v[36:37], v[24:25]
	v_sub_f32_e32 v56, v15, v82
	v_exp_f32_e32 v47, v55
	v_exp_f32_e32 v46, v48
	v_pk_add_f32 v[24:25], v[38:39], v[24:25]
	v_exp_f32_e64 v57, -v82
	v_exp_f32_e32 v49, v56
	v_exp_f32_e32 v48, v51
	v_pk_add_f32 v[24:25], v[40:41], v[24:25]
	v_mul_f32_e32 v0, 0, v57
	v_pk_add_f32 v[24:25], v[42:43], v[24:25]
	v_mov_b32_e32 v1, v0
	v_pk_add_f32 v[24:25], v[44:45], v[24:25]
	v_mov_b32_e32 v2, v0
	v_pk_add_f32 v[24:25], v[46:47], v[24:25]
	v_mov_b32_e32 v3, v0
	v_pk_add_f32 v[24:25], v[48:49], v[24:25]
	v_mov_b32_e32 v4, v0
	v_mov_b32_e32 v5, v0
	v_mov_b32_e32 v6, v0
	v_mov_b32_e32 v7, v0
	v_mov_b32_e32 v8, v0
	v_mov_b32_e32 v9, v0
	v_mov_b32_e32 v10, v0
	v_mov_b32_e32 v11, v0
	v_mov_b32_e32 v12, v0
	v_mov_b32_e32 v13, v0
	v_mov_b32_e32 v14, v0
	v_mov_b32_e32 v15, v0
	v_add_f32_e32 v163, v24, v25
	v_cvt_pk_bf16_f32 v78, v27, v29
	v_cvt_pk_bf16_f32 v79, v31, v33
	v_fmac_f32_e32 v163, 0, v57
	v_cvt_pk_bf16_f32 v72, v35, v37
	v_cvt_pk_bf16_f32 v73, v39, v41
	v_cvt_pk_bf16_f32 v74, v43, v45
	v_cvt_pk_bf16_f32 v75, v47, v49
	v_cvt_pk_bf16_f32 v70, v26, v28
	v_cvt_pk_bf16_f32 v71, v30, v32
	v_cvt_pk_bf16_f32 v64, v34, v36
	v_cvt_pk_bf16_f32 v65, v38, v40
	v_cvt_pk_bf16_f32 v66, v42, v44
	v_cvt_pk_bf16_f32 v67, v46, v48
	s_waitcnt lgkmcnt(2)
	v_mfma_f32_32x32x16_bf16 v[48:63], v[16:19], v[76:79], v[0:15]
	ds_read_b128 v[92:95], v165 offset:17440
	s_waitcnt lgkmcnt(2)
	v_mfma_f32_32x32x16_bf16 v[32:47], v[20:23], v[76:79], v[0:15]
	ds_read_b128 v[166:169], v165 offset:22048
	v_mfma_f32_32x32x16_bf16 v[16:31], v[84:87], v[76:79], v[0:15]
	ds_read_b128 v[84:87], v165 offset:26656
	s_waitcnt lgkmcnt(3)
	v_mfma_f32_32x32x16_bf16 v[0:15], v[88:91], v[76:79], v[0:15]
	ds_read_b128 v[76:79], v165 offset:31264
	s_waitcnt lgkmcnt(3)
	v_mfma_f32_32x32x16_bf16 v[48:63], v[92:95], v[72:75], v[48:63]
	ds_read_b128 v[88:91], v165 offset:17472
	s_waitcnt lgkmcnt(3)
	v_mfma_f32_32x32x16_bf16 v[32:47], v[166:169], v[72:75], v[32:47]
	ds_read_b128 v[92:95], v165 offset:22080
	s_waitcnt lgkmcnt(3)
	v_mfma_f32_32x32x16_bf16 v[16:31], v[84:87], v[72:75], v[16:31]
	ds_read_b128 v[84:87], v165 offset:26688
	s_waitcnt lgkmcnt(3)
	v_mfma_f32_32x32x16_bf16 v[0:15], v[76:79], v[72:75], v[0:15]
	ds_read_b128 v[72:75], v165 offset:31296
	s_waitcnt lgkmcnt(3)
	v_mfma_f32_32x32x16_bf16 v[48:63], v[88:91], v[68:71], v[48:63]
	ds_read_b128 v[76:79], v165 offset:17504
	s_waitcnt lgkmcnt(3)
	v_mfma_f32_32x32x16_bf16 v[32:47], v[92:95], v[68:71], v[32:47]
	ds_read_b128 v[88:91], v165 offset:22112
	s_waitcnt lgkmcnt(3)
	v_mfma_f32_32x32x16_bf16 v[16:31], v[84:87], v[68:71], v[16:31]
	ds_read_b128 v[84:87], v165 offset:26720
	s_waitcnt lgkmcnt(3)
	v_mfma_f32_32x32x16_bf16 v[0:15], v[72:75], v[68:71], v[0:15]
	ds_read_b128 v[68:71], v165 offset:31328
	s_waitcnt lgkmcnt(0)
	s_barrier
; #define MFMA(a, b, c) __builtin_amdgcn_mfma_f32_32x32x16_bf16((a), (b), (c), 0, 0, 0)
; DI void softmax_pv(f32x16 (&sa)[2], f32x16 (&O)[4], float& m, float& l, const char* sV, int lr, int lh, bool first) {
;     ...
;   for (int t = 0; t < 16; ++t) {
;     if (t + 3 < 16) {
;       vfr[(t + 3) & 3] = *(const bf16x8*)(vrd + ((t + 3) & 3) * (32 * 144) + ((t + 3) >> 2) * 32);
;       __builtin_amdgcn_sched_group_barrier(0x100, 1, 0);
;     }
;     O[t & 3] = MFMA(vfr[t & 3], pf[t >> 2], O[t & 3]);
;     __builtin_amdgcn_sched_group_barrier(0x008, 1, 0);
;   }
; }
; DI void diff_item(const Params& p, const GroupP& g, int l_layer, int item, char* smem, bool dry) {
;     ...
;     if (more) { storeK(); load_vtile(rv, vbase, Lp, (kt + 1) * 64, voffV); }
;     __builtin_amdgcn_sched_barrier(0);
;     softmax_pv(sa, O, m, l, sV, lr, lh, kt == 0);
;     __syncthreads();
;     if (more) store_vtile(rv, sV_st);
	v_mfma_f32_32x32x16_bf16 v[48:63], v[76:79], v[64:67], v[48:63]
	v_mfma_f32_32x32x16_bf16 v[32:47], v[88:91], v[64:67], v[32:47]
	v_mfma_f32_32x32x16_bf16 v[16:31], v[84:87], v[64:67], v[16:31]
	v_mfma_f32_32x32x16_bf16 v[0:15], v[68:71], v[64:67], v[0:15]
	s_cbranch_vccnz .LBB0_206
	s_lshl_b32 s4, s48, 6
	v_add_u32_e32 v64, v80, v81
	s_or_b32 s5, s4, s47
	v_add_u32_e32 v167, 0x4000, v64
	v_add_u32_e32 v168, 0x5000, v64
	v_add_u32_e32 v169, 0x6800, v64
	v_add_u32_e32 v170, 0x7800, v64
	v_add_u32_e32 v64, s5, v154
	v_readlane_b32 s5, v255, 50
	s_mul_i32 s5, s5, s49
	v_readlane_b32 s8, v255, 51
	v_sub_u32_e32 v64, s5, v64
	s_sub_i32 s5, s5, s47
	s_sub_i32 s4, s5, s4
	s_add_u32 s5, s42, s94
	s_addc_u32 s9, s43, 0
	s_add_u32 s8, s8, s5
	v_readlane_b32 s5, v255, 52
	s_addc_u32 s9, s5, s9
	v_add_f32_e32 v166, 0, v82
	v_add_u32_e32 v171, v156, v64
	v_lshl_add_u64 v[152:153], s[8:9], 0, v[184:185]
	s_mov_b32 s5, 0
	s_movk_i32 s94, 0x100
	s_mov_b32 s42, 0
	v_readlane_b32 s43, v255, 34
	s_waitcnt vmcnt(3)
	ds_write2_b64 v167, v[120:121], v[122:123] offset0:128 offset1:130
	s_waitcnt vmcnt(2)
	ds_write2_b64 v168, v[124:125], v[126:127] offset0:192 offset1:194
	s_waitcnt vmcnt(1)
	ds_write2_b64 v169, v[128:129], v[130:131] offset1:2
	s_waitcnt vmcnt(0)
	ds_write2_b64 v170, v[132:133], v[134:135] offset0:64 offset1:66
	v_mov_b32_e32 v218, 0x7fc00000
	s_branch .LBB0_194

; #define MFMA(a, b, c) __builtin_amdgcn_mfma_f32_32x32x16_bf16((a), (b), (c), 0, 0, 0)
; DI void diff_item(const Params& p, const GroupP& g, int l_layer, int item, char* smem, bool dry) {
;     ...
;     for (int i = 0; i < 16; ++i) { sa[0][i] = binit; sa[1][i] = binit; }
;     {
;       const char* krd = sK + lr * 272 + map * 128 + lh * 16;
;       bf16x8 kf[4][2];
; #pragma unroll
;       for (int ks = 0; ks < 4; ++ks) {
;         kf[ks][0] = *(const bf16x8*)(krd + ks * 32);
;         kf[ks][1] = *(const bf16x8*)(krd + 32 * 272 + ks * 32);
;       }
; #pragma unroll
;       for (int ks = 0; ks < 4; ++ks) {
;         sa[0] = MFMA(kf[ks][0], qf[ks], sa[0]);
;         sa[1] = MFMA(kf[ks][1], qf[ks], sa[1]);
;       }
.Ldsd1_keep:
	s_addk_i32 s10, 0xffa1
	s_waitcnt lgkmcnt(3)
	v_mfma_f32_32x32x16_bf16 v[80:95], v[172:175], v[96:99], v[218:233]
	s_waitcnt lgkmcnt(2)
	v_mfma_f32_32x32x16_bf16 v[64:79], v[176:179], v[96:99], v[218:233]
	s_add_i32 s100, s42, 2
	s_cmp_ge_i32 s100, s33
	s_cbranch_scc1 .Ldqk1_nokld
	s_mov_b64 s[100:101], 0x4000
	global_load_dwordx4 v[116:119], v[152:153], off
	v_lshl_add_u64 v[112:113], v[152:153], 0, s[100:101]
	v_lshl_add_u64 v[136:137], v[112:113], 0, s[100:101]
	v_lshl_add_u64 v[140:141], v[136:137], 0, s[100:101]
	global_load_dwordx4 v[112:115], v[112:113], off
	global_load_dwordx4 v[136:139], v[136:137], off
	global_load_dwordx4 v[140:143], v[140:141], off

; template <bool SWAP, bool SSQ, class AF>
; DI void gemm_main(AF asrc, int m0, const u16* __restrict__ Bw, int ldb, int K, char* smem,
;                   f32x16 (&acc)[4][2], float ssq_eps, float (&rs)[4]) {
;     ...
;   auto gload = [&](int kt) {
;     ASrc s = asrc(kt);
;     const unsigned voffA = (unsigned)(srow * (int)s.ld * 2 + skc * 16);
;     const char* ua = (const char*)s.p + (long)m0 * s.ld * 2;
; #pragma unroll
;     for (int i = 0; i < 8; ++i) ra[i] = *(const u32x4*)(ua + (long)(32 * i) * s.ld * 2 + voffA);
;     const char* ub = (const char*)Bw + (long)kt * 128;
; #pragma unroll
;     for (int i = 0; i < 4; ++i) rb[i] = *(const u32x4*)(ub + (long)(32 * i) * ldb * 2 + voffB);
;   };
;   auto sstore = [&]() {
; #pragma unroll
;     for (int i = 0; i < 8; ++i) *(u32x4*)(sA + lds_st + i * (32 * 144)) = ra[i];
; #pragma unroll
;     for (int i = 0; i < 4; ++i) *(u32x4*)(sB + lds_st + i * (32 * 144)) = rb[i];
;   };
;   const int nkt = K >> 6;
;   const char* pA = sA + (wm * 128 + lr) * 144 + lh * 16;
;   const char* pB = sB + (wn * 64 + lr) * 144 + lh * 16;
;   gload(0);
;   sstore();
; DI void phase_outproj(const Params& p, const GroupP& g, int l, char* smem, int vb) {
;     ...
;   for (int it = vb; it < ((ntiles + 7) & ~7); it += gridDim.x) {
;     const int tt = xcd_tile(it, ntiles);
;     if (tt < 0) continue;
;     int nt, mt;
;     tile_mn(tt, nmt, 16, mt, nt);
;     int m0 = mt * 256, n0 = nt * 128;
.LBB0_906:
	s_lshr_b32 s7, s6, 4
	s_and_b32 s7, s7, 0x7fffffc
	s_sub_i32 s8, s30, s7
	s_min_i32 s8, s8, 4
	s_abs_i32 s9, s8
	v_cvt_f32_u32_e32 v0, s9
	s_sub_i32 s11, 0, s9
	s_and_b32 s6, s6, 63
	s_ashr_i32 s10, s8, 31
	v_rcp_iflag_f32_e32 v0, v0
	v_readlane_b32 s16, v254, 36
	v_mov_b32_e32 v50, v200
	v_readlane_b32 s17, v254, 37
	v_mul_f32_e32 v0, 0x4f7ffffe, v0
	v_cvt_u32_f32_e32 v0, v0
	s_load_dwordx16 s[44:59], s[16:17], 0xb8
	v_readfirstlane_b32 s22, v50
	v_readfirstlane_b32 s12, v0
	s_mul_i32 s11, s11, s12
	s_mul_hi_u32 s11, s12, s11
	s_add_i32 s12, s12, s11
	s_mul_hi_u32 s11, s6, s12
	s_mul_i32 s12, s11, s9
	s_sub_i32 s12, s6, s12
	s_add_i32 s13, s11, 1
	s_sub_i32 s14, s12, s9
	s_cmp_ge_u32 s12, s9
	s_cselect_b32 s11, s13, s11
	s_cselect_b32 s12, s14, s12
	s_add_i32 s13, s11, 1
	s_cmp_ge_u32 s12, s9
	s_cselect_b32 s9, s13, s11
	s_add_i32 s7, s7, s6
	s_xor_b32 s6, s9, s10
	s_sub_i32 s6, s6, s10
	s_mul_i32 s8, s6, s8
	s_lshl_b32 s6, s6, 7
	s_sub_i32 s8, s7, s8
	s_ashr_i32 s7, s6, 31
	s_lshl_b32 s8, s8, 8
	s_lshl_b64 s[12:13], s[6:7], 12
	s_add_u32 s10, s26, s12
	s_addc_u32 s11, s27, s13
	s_ashr_i32 s9, s8, 31
	v_lshlrev_b32_e32 v0, 4, v50
	s_and_b32 s23, s22, 0xfffff80
	s_lshl_b64 s[14:15], s[8:9], 10
	v_ashrrev_i32_e32 v51, 3, v50
	s_waitcnt vmcnt(0)
	v_and_b32_e32 v132, 0x70, v0
	s_waitcnt lgkmcnt(0)
	s_add_u32 s14, s46, s14
	v_lshl_or_b32 v184, v51, 10, v132
	s_addc_u32 s15, s47, s15
	v_lshl_add_u64 v[28:29], s[14:15], 0, v[184:185]
	s_mov_b32 s7, 0x8000
	v_add_co_u32_e32 v4, vcc, s7, v28
	s_mov_b32 s7, 0x10000
	s_nop 0
	v_addc_co_u32_e32 v5, vcc, 0, v29, vcc
	v_add_co_u32_e32 v8, vcc, s7, v28
	s_mov_b32 s7, 0x18000
	s_nop 0
	v_addc_co_u32_e32 v9, vcc, 0, v29, vcc
	v_add_co_u32_e32 v12, vcc, s7, v28
	s_mov_b32 s7, 0x30000
	s_nop 0
	v_addc_co_u32_e32 v13, vcc, 0, v29, vcc
	v_add_co_u32_e32 v16, vcc, s75, v28
	v_lshl_or_b32 v48, v51, 12, v132
	s_nop 0
	v_addc_co_u32_e32 v17, vcc, 0, v29, vcc
	v_add_co_u32_e32 v20, vcc, s65, v28
	v_mov_b32_e32 v49, v185
	s_nop 0
	v_addc_co_u32_e32 v21, vcc, 0, v29, vcc
	v_add_co_u32_e32 v24, vcc, s7, v28
	s_mov_b32 s7, 0x38000
	s_nop 0
	v_addc_co_u32_e32 v25, vcc, 0, v29, vcc
	v_add_co_u32_e32 v28, vcc, s7, v28
	v_lshl_add_u64 v[44:45], s[10:11], 0, v[48:49]
	s_nop 0
	v_addc_co_u32_e32 v29, vcc, 0, v29, vcc
	v_add_co_u32_e32 v36, vcc, s75, v44
	s_mov_b32 s7, 0x40000
	s_nop 0
	v_addc_co_u32_e32 v37, vcc, 0, v45, vcc
	v_add_co_u32_e32 v40, vcc, s7, v44
	global_load_dwordx4 v[0:3], v184, s[14:15]
	s_nop 0
	v_addc_co_u32_e32 v41, vcc, 0, v45, vcc
	global_load_dwordx4 v[4:7], v[4:5], off
	s_nop 0
	global_load_dwordx4 v[8:11], v[8:9], off
	s_nop 0
	global_load_dwordx4 v[12:15], v[12:13], off
	s_nop 0
	global_load_dwordx4 v[16:19], v[16:17], off
	s_nop 0
	global_load_dwordx4 v[20:23], v[20:21], off
	s_nop 0
	global_load_dwordx4 v[24:27], v[24:25], off
	s_mov_b32 s7, 0x60000
	global_load_dwordx4 v[28:31], v[28:29], off
	v_add_co_u32_e32 v44, vcc, s7, v44
	global_load_dwordx4 v[32:35], v48, s[10:11]
	s_nop 0
	global_load_dwordx4 v[36:39], v[36:37], off
	s_nop 0
	global_load_dwordx4 v[40:43], v[40:41], off
	v_addc_co_u32_e32 v45, vcc, 0, v45, vcc
	global_load_dwordx4 v[44:47], v[44:45], off
	v_mad_u64_u32 v[134:135], s[10:11], v51, s64, v[132:133]
	v_and_b32_e32 v52, 31, v50
	s_lshl_b64 s[10:11], s[8:9], 1
	v_lshrrev_b32_e32 v50, 1, v50
	v_and_or_b32 v53, s22, 64, v52
	v_or_b32_e32 v52, s23, v52
	s_add_u32 s12, s37, s12
	v_and_b32_e32 v50, 16, v50
	v_mul_u32_u24_e32 v53, 0x90, v53
	v_mul_lo_u32 v52, v52, s64
	s_addc_u32 s13, s38, s13
	s_mov_b32 s42, 0
	s_mov_b32 s7, 64
	v_lshlrev_b32_e32 v139, 1, v51
	v_lshl_add_u64 v[136:137], s[12:13], 0, v[48:49]
	s_mov_b64 s[12:13], 0
	v_add_u32_e32 v133, v52, v50
	v_add_u32_e32 v135, v53, v50
	s_waitcnt vmcnt(11)
	ds_write_b128 v134, v[0:3]
	s_waitcnt vmcnt(10)
; template <bool SWAP, bool SSQ, class AF>
; DI void gemm_main(AF asrc, int m0, const u16* __restrict__ Bw, int ldb, int K, char* smem,
;                   f32x16 (&acc)[4][2], float ssq_eps, float (&rs)[4]) {
;     ...
;   for (int mi = 0; mi < 4; ++mi)
; #pragma unroll
;     for (int ni = 0; ni < 2; ++ni)
; #pragma unroll
;       for (int i = 0; i < 16; ++i) acc[mi][ni][i] = 0.f;
;   auto gload = [&](int kt) {
;     ASrc s = asrc(kt);
;     const unsigned voffA = (unsigned)(srow * (int)s.ld * 2 + skc * 16);
;     const char* ua = (const char*)s.p + (long)m0 * s.ld * 2;
; #pragma unroll
;     for (int i = 0; i < 8; ++i) ra[i] = *(const u32x4*)(ua + (long)(32 * i) * s.ld * 2 + voffA);
;     const char* ub = (const char*)Bw + (long)kt * 128;
; #pragma unroll
;     for (int i = 0; i < 4; ++i) rb[i] = *(const u32x4*)(ub + (long)(32 * i) * ldb * 2 + voffB);
;   };
;   auto sstore = [&]() {
; #pragma unroll
;     for (int i = 0; i < 8; ++i) *(u32x4*)(sA + lds_st + i * (32 * 144)) = ra[i];
; #pragma unroll
;     for (int i = 0; i < 4; ++i) *(u32x4*)(sB + lds_st + i * (32 * 144)) = rb[i];
;   };
;   const int nkt = K >> 6;
;   const char* pA = sA + (wm * 128 + lr) * 144 + lh * 16;
;   const char* pB = sB + (wn * 64 + lr) * 144 + lh * 16;
;   gload(0);
;   sstore();
;   __syncthreads();
	ds_write_b128 v134, v[4:7] offset:4608
	s_waitcnt vmcnt(9)
	ds_write_b128 v134, v[8:11] offset:9216
	s_waitcnt vmcnt(8)
	ds_write_b128 v134, v[12:15] offset:13824
	s_waitcnt vmcnt(7)
	ds_write_b128 v134, v[16:19] offset:18432
	s_waitcnt vmcnt(6)
	ds_write_b128 v134, v[20:23] offset:23040
	s_waitcnt vmcnt(5)
	ds_write_b128 v134, v[24:27] offset:27648
	s_waitcnt vmcnt(4)
	ds_write_b128 v134, v[28:31] offset:32256
	s_waitcnt vmcnt(3)
	ds_write_b128 v134, v[32:35] offset:36864
	s_waitcnt vmcnt(2)
	ds_write_b128 v134, v[36:39] offset:41472
	s_waitcnt vmcnt(1)
	ds_write_b128 v134, v[40:43] offset:46080
	s_waitcnt vmcnt(0)
	ds_write_b128 v134, v[44:47] offset:50688
	v_mov_b32_e32 v0, 0
	v_mov_b32_e32 v1, v0
	v_mov_b32_e32 v2, v0
	v_mov_b32_e32 v3, v0
	v_mov_b32_e32 v4, v0
	v_mov_b32_e32 v5, v0
	v_mov_b32_e32 v6, v0
	v_mov_b32_e32 v7, v0
	v_mov_b32_e32 v8, v0
	v_mov_b32_e32 v9, v0
	v_mov_b32_e32 v10, v0
	v_mov_b32_e32 v11, v0
	v_mov_b32_e32 v12, v0
	v_mov_b32_e32 v13, v0
	v_mov_b32_e32 v14, v0
	v_mov_b32_e32 v15, v0
	v_mov_b32_e32 v16, v0
	v_mov_b32_e32 v17, v0
	v_mov_b32_e32 v18, v0
	v_mov_b32_e32 v19, v0
	v_mov_b32_e32 v20, v0
	v_mov_b32_e32 v21, v0
	v_mov_b32_e32 v22, v0
	v_mov_b32_e32 v23, v0
	v_mov_b32_e32 v24, v0
	v_mov_b32_e32 v25, v0
	v_mov_b32_e32 v26, v0
	v_mov_b32_e32 v27, v0
	v_mov_b32_e32 v28, v0
	v_mov_b32_e32 v29, v0
	v_mov_b32_e32 v30, v0
	v_mov_b32_e32 v31, v0
	v_mov_b32_e32 v32, v0
	v_mov_b32_e32 v33, v0
	v_mov_b32_e32 v34, v0
	v_mov_b32_e32 v35, v0
	v_mov_b32_e32 v36, v0
	v_mov_b32_e32 v37, v0
	v_mov_b32_e32 v38, v0
	v_mov_b32_e32 v39, v0
	v_mov_b32_e32 v40, v0
	v_mov_b32_e32 v41, v0
	v_mov_b32_e32 v42, v0
	v_mov_b32_e32 v43, v0
	v_mov_b32_e32 v44, v0
	v_mov_b32_e32 v45, v0
	v_mov_b32_e32 v46, v0
	v_mov_b32_e32 v47, v0
	v_mov_b32_e32 v48, v0
	v_mov_b32_e32 v49, v0
	v_mov_b32_e32 v50, v0
	v_mov_b32_e32 v51, v0
	v_mov_b32_e32 v52, v0
	v_mov_b32_e32 v53, v0
	v_mov_b32_e32 v54, v0
	v_mov_b32_e32 v55, v0
	v_mov_b32_e32 v56, v0
	v_mov_b32_e32 v57, v0
	v_mov_b32_e32 v58, v0
	v_mov_b32_e32 v59, v0
	v_mov_b32_e32 v60, v0
	v_mov_b32_e32 v61, v0
	v_mov_b32_e32 v62, v0
	v_mov_b32_e32 v63, v0
	v_mov_b32_e32 v64, v0
	v_mov_b32_e32 v65, v0
	v_mov_b32_e32 v66, v0
	v_mov_b32_e32 v67, v0
	v_mov_b32_e32 v68, v0
	v_mov_b32_e32 v69, v0
	v_mov_b32_e32 v70, v0
	v_mov_b32_e32 v71, v0
	v_mov_b32_e32 v72, v0
	v_mov_b32_e32 v73, v0
	v_mov_b32_e32 v74, v0
	v_mov_b32_e32 v75, v0
	v_mov_b32_e32 v76, v0
	v_mov_b32_e32 v77, v0
	v_mov_b32_e32 v78, v0
	v_mov_b32_e32 v79, v0
	v_mov_b32_e32 v80, v0
	v_mov_b32_e32 v81, v0
	v_mov_b32_e32 v82, v0
	v_mov_b32_e32 v83, v0
	v_mov_b32_e32 v84, v0
	v_mov_b32_e32 v85, v0
	v_mov_b32_e32 v86, v0
	v_mov_b32_e32 v87, v0
	v_mov_b32_e32 v88, v0
	v_mov_b32_e32 v89, v0
	v_mov_b32_e32 v90, v0
	v_mov_b32_e32 v91, v0
	v_mov_b32_e32 v92, v0
	v_mov_b32_e32 v93, v0
	v_mov_b32_e32 v94, v0
	v_mov_b32_e32 v95, v0
	v_mov_b32_e32 v96, v0
	v_mov_b32_e32 v97, v0
	v_mov_b32_e32 v98, v0
	v_mov_b32_e32 v99, v0
	v_mov_b32_e32 v100, v0
	v_mov_b32_e32 v101, v0
	v_mov_b32_e32 v102, v0
	v_mov_b32_e32 v103, v0
	v_mov_b32_e32 v104, v0
	v_mov_b32_e32 v105, v0
	v_mov_b32_e32 v106, v0
	v_mov_b32_e32 v107, v0
	v_mov_b32_e32 v108, v0
	v_mov_b32_e32 v109, v0
	v_mov_b32_e32 v110, v0
	v_mov_b32_e32 v111, v0
	v_mov_b32_e32 v112, v0
	v_mov_b32_e32 v113, v0
	v_mov_b32_e32 v114, v0
	v_mov_b32_e32 v115, v0
	v_mov_b32_e32 v116, v0
	v_mov_b32_e32 v117, v0
	v_mov_b32_e32 v118, v0
	v_mov_b32_e32 v119, v0
	v_mov_b32_e32 v120, v0
	v_mov_b32_e32 v121, v0
	v_mov_b32_e32 v122, v0
	v_mov_b32_e32 v123, v0
	v_mov_b32_e32 v124, v0
	v_mov_b32_e32 v125, v0
	v_mov_b32_e32 v126, v0
	v_mov_b32_e32 v127, v0
	v_readlane_b32 s16, v254, 36
	v_readlane_b32 s17, v254, 37
	s_nop 0
	s_load_dwordx2 s[54:55], s[16:17], 0xe0
	s_load_dwordx2 s[46:47], s[16:17], 0x100
	s_waitcnt lgkmcnt(0)
	s_barrier
	s_branch .LBB0_908

; DI void phase_outproj(const Params& p, const GroupP& g, int l, char* smem, int vb) {
;     ...
;         [&](int kt) {
;           int k0 = kt * 64;
;           if (k0 < 512) return ASrc{uf + k0, 512};
;           if (k0 < 1536) { int kk = k0 - 512; return ASrc{q + (kk >> 7) * 192 + (kk & 127), 1536}; }
;           return ASrc{qd + (k0 - 1536), 512};
;         },
.LBB0_908:
	s_add_i32 s9, s42, 1
	s_cmp_gt_u32 s42, 6
	s_mov_b64 s[24:25], -1
	s_cbranch_scc0 .LBB0_914
	s_cmp_gt_u32 s42, 22
	s_mov_b64 s[22:23], -1
	s_cbranch_scc0 .LBB0_911
	s_lshl_b32 s14, s9, 7
	s_mov_b64 s[22:23], 0
	s_add_u32 s14, s54, s14
	s_addc_u32 s15, s55, 0
	s_add_u32 s14, s14, 0xfffff400
	s_addc_u32 s15, s15, -1
.LBB0_911:
	s_andn2_b64 vcc, exec, s[22:23]
	s_mov_b64 s[22:23], 0x200
	s_cbranch_vccnz .LBB0_913
	s_add_i32 s14, s7, 0xfffffe00
	s_lshr_b32 s14, s14, 7
	s_mul_i32 s94, s14, 0xc0
	s_lshl_b64 s[14:15], s[94:95], 1
	s_mov_b64 s[42:43], s[46:47]
	s_add_u32 s14, s42, s14
	s_addc_u32 s15, s43, s15
	s_and_b32 s22, s7, 64
	s_lshl_b32 s22, s22, 1
	s_add_u32 s14, s14, s22
	s_addc_u32 s15, s15, 0
	s_mov_b64 s[22:23], 0x600

; template <bool SWAP, bool SSQ, class AF>
; DI void gemm_main(AF asrc, int m0, const u16* __restrict__ Bw, int ldb, int K, char* smem,
;                   f32x16 (&acc)[4][2], float ssq_eps, float (&rs)[4]) {
;     ...
;   auto gload = [&](int kt) {
;     ASrc s = asrc(kt);
;     const unsigned voffA = (unsigned)(srow * (int)s.ld * 2 + skc * 16);
;     const char* ua = (const char*)s.p + (long)m0 * s.ld * 2;
; #pragma unroll
;     for (int i = 0; i < 8; ++i) ra[i] = *(const u32x4*)(ua + (long)(32 * i) * s.ld * 2 + voffA);
;     const char* ub = (const char*)Bw + (long)kt * 128;
; #pragma unroll
;     for (int i = 0; i < 4; ++i) rb[i] = *(const u32x4*)(ub + (long)(32 * i) * ldb * 2 + voffB);
;   };
;   auto sstore = [&]() {
; #pragma unroll
;     for (int i = 0; i < 8; ++i) *(u32x4*)(sA + lds_st + i * (32 * 144)) = ra[i];
; #pragma unroll
;     for (int i = 0; i < 4; ++i) *(u32x4*)(sB + lds_st + i * (32 * 144)) = rb[i];
;   };
;   const int nkt = K >> 6;
;   const char* pA = sA + (wm * 128 + lr) * 144 + lh * 16;
;   const char* pB = sB + (wn * 64 + lr) * 144 + lh * 16;
;   gload(0);
;   sstore();
;   __syncthreads();
; DI void phase_outproj(const Params& p, const GroupP& g, int l, char* smem, int vb) {
;     ...
;   for (int it = vb; it < ((ntiles + 7) & ~7); it += gridDim.x) {
;     const int tt = xcd_tile(it, ntiles);
;     if (tt < 0) continue;
;     int nt, mt;
;     tile_mn(tt, nmt, 16, mt, nt);
;     int m0 = mt * 256, n0 = nt * 128;
.LBB0_963:
	s_lshr_b32 s7, s6, 4
	s_and_b32 s7, s7, 0x7fffffc
	s_sub_i32 s8, s30, s7
	s_min_i32 s8, s8, 4
	s_abs_i32 s9, s8
	v_cvt_f32_u32_e32 v0, s9
	s_sub_i32 s11, 0, s9
	s_and_b32 s6, s6, 63
	s_ashr_i32 s10, s8, 31
	v_rcp_iflag_f32_e32 v0, v0
	v_readlane_b32 s16, v254, 36
	v_mov_b32_e32 v50, v200
	v_readlane_b32 s17, v254, 37
	v_mul_f32_e32 v0, 0x4f7ffffe, v0
	v_cvt_u32_f32_e32 v0, v0
	s_load_dwordx16 s[44:59], s[16:17], 0x28
	v_readfirstlane_b32 s22, v50
	v_readfirstlane_b32 s12, v0
	s_mul_i32 s11, s11, s12
	s_mul_hi_u32 s11, s12, s11
	s_add_i32 s12, s12, s11
	s_mul_hi_u32 s11, s6, s12
	s_mul_i32 s12, s11, s9
	s_sub_i32 s12, s6, s12
	s_add_i32 s13, s11, 1
	s_sub_i32 s14, s12, s9
	s_cmp_ge_u32 s12, s9
	s_cselect_b32 s11, s13, s11
	s_cselect_b32 s12, s14, s12
	s_add_i32 s13, s11, 1
	s_cmp_ge_u32 s12, s9
	s_cselect_b32 s9, s13, s11
	s_add_i32 s7, s7, s6
	s_xor_b32 s6, s9, s10
	s_sub_i32 s6, s6, s10
	s_mul_i32 s8, s6, s8
	s_lshl_b32 s6, s6, 7
	s_sub_i32 s8, s7, s8
	s_ashr_i32 s7, s6, 31
	s_lshl_b32 s8, s8, 8
	s_lshl_b64 s[12:13], s[6:7], 12
	s_add_u32 s10, s26, s12
	s_addc_u32 s11, s27, s13
	s_ashr_i32 s9, s8, 31
	v_lshlrev_b32_e32 v0, 4, v50
	s_and_b32 s23, s22, 0xfffff80
	s_lshl_b64 s[14:15], s[8:9], 10
	v_ashrrev_i32_e32 v51, 3, v50
	s_waitcnt vmcnt(0)
	v_and_b32_e32 v132, 0x70, v0
	s_waitcnt lgkmcnt(0)
	s_add_u32 s14, s46, s14
	v_lshl_or_b32 v184, v51, 10, v132
	s_addc_u32 s15, s47, s15
	v_lshl_add_u64 v[28:29], s[14:15], 0, v[184:185]
	s_mov_b32 s7, 0x8000
	v_add_co_u32_e32 v4, vcc, s7, v28
	s_mov_b32 s7, 0x10000
	s_nop 0
	v_addc_co_u32_e32 v5, vcc, 0, v29, vcc
	v_add_co_u32_e32 v8, vcc, s7, v28
	s_mov_b32 s7, 0x18000
	s_nop 0
	v_addc_co_u32_e32 v9, vcc, 0, v29, vcc
	v_add_co_u32_e32 v12, vcc, s7, v28
	s_mov_b32 s7, 0x30000
	s_nop 0
	v_addc_co_u32_e32 v13, vcc, 0, v29, vcc
	v_add_co_u32_e32 v16, vcc, s75, v28
	v_lshl_or_b32 v48, v51, 12, v132
	s_nop 0
	v_addc_co_u32_e32 v17, vcc, 0, v29, vcc
	v_add_co_u32_e32 v20, vcc, s65, v28
	v_mov_b32_e32 v49, v185
	s_nop 0
	v_addc_co_u32_e32 v21, vcc, 0, v29, vcc
	v_add_co_u32_e32 v24, vcc, s7, v28
	s_mov_b32 s7, 0x38000
	s_nop 0
	v_addc_co_u32_e32 v25, vcc, 0, v29, vcc
	v_add_co_u32_e32 v28, vcc, s7, v28
	v_lshl_add_u64 v[44:45], s[10:11], 0, v[48:49]
	s_nop 0
	v_addc_co_u32_e32 v29, vcc, 0, v29, vcc
	v_add_co_u32_e32 v36, vcc, s75, v44
	s_mov_b32 s7, 0x40000
	s_nop 0
	v_addc_co_u32_e32 v37, vcc, 0, v45, vcc
	v_add_co_u32_e32 v40, vcc, s7, v44
	global_load_dwordx4 v[0:3], v184, s[14:15]
	s_nop 0
	v_addc_co_u32_e32 v41, vcc, 0, v45, vcc
	global_load_dwordx4 v[4:7], v[4:5], off
	s_nop 0
	global_load_dwordx4 v[8:11], v[8:9], off
	s_nop 0
	global_load_dwordx4 v[12:15], v[12:13], off
	s_nop 0
	global_load_dwordx4 v[16:19], v[16:17], off
	s_nop 0
	global_load_dwordx4 v[20:23], v[20:21], off
	s_nop 0
	global_load_dwordx4 v[24:27], v[24:25], off
	s_mov_b32 s7, 0x60000
	global_load_dwordx4 v[28:31], v[28:29], off
	v_add_co_u32_e32 v44, vcc, s7, v44
	global_load_dwordx4 v[32:35], v48, s[10:11]
	s_nop 0
	global_load_dwordx4 v[36:39], v[36:37], off
	s_nop 0
	global_load_dwordx4 v[40:43], v[40:41], off
	v_addc_co_u32_e32 v45, vcc, 0, v45, vcc
	global_load_dwordx4 v[44:47], v[44:45], off
	v_mad_u64_u32 v[134:135], s[10:11], v51, s64, v[132:133]
	v_and_b32_e32 v52, 31, v50
	s_lshl_b64 s[10:11], s[8:9], 1
	v_lshrrev_b32_e32 v50, 1, v50
	v_and_or_b32 v53, s22, 64, v52
	v_or_b32_e32 v52, s23, v52
	s_add_u32 s12, s28, s12
	v_and_b32_e32 v50, 16, v50
	v_mul_u32_u24_e32 v53, 0x90, v53
	v_mul_lo_u32 v52, v52, s64
	s_addc_u32 s13, s38, s13
	s_mov_b32 s41, 0
	s_mov_b32 s7, 64
	v_lshlrev_b32_e32 v139, 1, v51
	v_lshl_add_u64 v[136:137], s[12:13], 0, v[48:49]
	s_mov_b64 s[12:13], 0
	v_add_u32_e32 v133, v52, v50
	v_add_u32_e32 v135, v53, v50
	s_waitcnt vmcnt(11)
	ds_write_b128 v134, v[0:3]
	s_waitcnt vmcnt(10)
; template <bool SWAP, bool SSQ, class AF>
; DI void gemm_main(AF asrc, int m0, const u16* __restrict__ Bw, int ldb, int K, char* smem,
;                   f32x16 (&acc)[4][2], float ssq_eps, float (&rs)[4]) {
;     ...
;   for (int mi = 0; mi < 4; ++mi)
; #pragma unroll
;     for (int ni = 0; ni < 2; ++ni)
; #pragma unroll
;       for (int i = 0; i < 16; ++i) acc[mi][ni][i] = 0.f;
;   auto gload = [&](int kt) {
;     ASrc s = asrc(kt);
;     const unsigned voffA = (unsigned)(srow * (int)s.ld * 2 + skc * 16);
;     const char* ua = (const char*)s.p + (long)m0 * s.ld * 2;
; #pragma unroll
;     for (int i = 0; i < 8; ++i) ra[i] = *(const u32x4*)(ua + (long)(32 * i) * s.ld * 2 + voffA);
;     const char* ub = (const char*)Bw + (long)kt * 128;
; #pragma unroll
;     for (int i = 0; i < 4; ++i) rb[i] = *(const u32x4*)(ub + (long)(32 * i) * ldb * 2 + voffB);
;   };
;   auto sstore = [&]() {
; #pragma unroll
;     for (int i = 0; i < 8; ++i) *(u32x4*)(sA + lds_st + i * (32 * 144)) = ra[i];
; #pragma unroll
;     for (int i = 0; i < 4; ++i) *(u32x4*)(sB + lds_st + i * (32 * 144)) = rb[i];
;   };
;   const int nkt = K >> 6;
;   const char* pA = sA + (wm * 128 + lr) * 144 + lh * 16;
;   const char* pB = sB + (wn * 64 + lr) * 144 + lh * 16;
;   gload(0);
;   sstore();
;   __syncthreads();
	ds_write_b128 v134, v[4:7] offset:4608
	s_waitcnt vmcnt(9)
	ds_write_b128 v134, v[8:11] offset:9216
	s_waitcnt vmcnt(8)
	ds_write_b128 v134, v[12:15] offset:13824
	s_waitcnt vmcnt(7)
	ds_write_b128 v134, v[16:19] offset:18432
	s_waitcnt vmcnt(6)
	ds_write_b128 v134, v[20:23] offset:23040
	s_waitcnt vmcnt(5)
	ds_write_b128 v134, v[24:27] offset:27648
	s_waitcnt vmcnt(4)
	ds_write_b128 v134, v[28:31] offset:32256
	s_waitcnt vmcnt(3)
	ds_write_b128 v134, v[32:35] offset:36864
	s_waitcnt vmcnt(2)
	ds_write_b128 v134, v[36:39] offset:41472
	s_waitcnt vmcnt(1)
	ds_write_b128 v134, v[40:43] offset:46080
	s_waitcnt vmcnt(0)
	ds_write_b128 v134, v[44:47] offset:50688
	v_mov_b32_e32 v0, 0
	v_mov_b32_e32 v1, v0
	v_mov_b32_e32 v2, v0
	v_mov_b32_e32 v3, v0
	v_mov_b32_e32 v4, v0
	v_mov_b32_e32 v5, v0
	v_mov_b32_e32 v6, v0
	v_mov_b32_e32 v7, v0
	v_mov_b32_e32 v8, v0
	v_mov_b32_e32 v9, v0
	v_mov_b32_e32 v10, v0
	v_mov_b32_e32 v11, v0
	v_mov_b32_e32 v12, v0
	v_mov_b32_e32 v13, v0
	v_mov_b32_e32 v14, v0
	v_mov_b32_e32 v15, v0
	v_mov_b32_e32 v16, v0
	v_mov_b32_e32 v17, v0
	v_mov_b32_e32 v18, v0
	v_mov_b32_e32 v19, v0
	v_mov_b32_e32 v20, v0
	v_mov_b32_e32 v21, v0
	v_mov_b32_e32 v22, v0
	v_mov_b32_e32 v23, v0
	v_mov_b32_e32 v24, v0
	v_mov_b32_e32 v25, v0
	v_mov_b32_e32 v26, v0
	v_mov_b32_e32 v27, v0
	v_mov_b32_e32 v28, v0
	v_mov_b32_e32 v29, v0
	v_mov_b32_e32 v30, v0
	v_mov_b32_e32 v31, v0
	v_mov_b32_e32 v32, v0
	v_mov_b32_e32 v33, v0
	v_mov_b32_e32 v34, v0
	v_mov_b32_e32 v35, v0
	v_mov_b32_e32 v36, v0
	v_mov_b32_e32 v37, v0
	v_mov_b32_e32 v38, v0
	v_mov_b32_e32 v39, v0
	v_mov_b32_e32 v40, v0
	v_mov_b32_e32 v41, v0
	v_mov_b32_e32 v42, v0
	v_mov_b32_e32 v43, v0
	v_mov_b32_e32 v44, v0
	v_mov_b32_e32 v45, v0
	v_mov_b32_e32 v46, v0
	v_mov_b32_e32 v47, v0
	v_mov_b32_e32 v48, v0
	v_mov_b32_e32 v49, v0
	v_mov_b32_e32 v50, v0
	v_mov_b32_e32 v51, v0
	v_mov_b32_e32 v52, v0
	v_mov_b32_e32 v53, v0
	v_mov_b32_e32 v54, v0
	v_mov_b32_e32 v55, v0
	v_mov_b32_e32 v56, v0
	v_mov_b32_e32 v57, v0
	v_mov_b32_e32 v58, v0
	v_mov_b32_e32 v59, v0
	v_mov_b32_e32 v60, v0
	v_mov_b32_e32 v61, v0
	v_mov_b32_e32 v62, v0
	v_mov_b32_e32 v63, v0
	v_mov_b32_e32 v64, v0
	v_mov_b32_e32 v65, v0
	v_mov_b32_e32 v66, v0
	v_mov_b32_e32 v67, v0
	v_mov_b32_e32 v68, v0
	v_mov_b32_e32 v69, v0
	v_mov_b32_e32 v70, v0
	v_mov_b32_e32 v71, v0
	v_mov_b32_e32 v72, v0
	v_mov_b32_e32 v73, v0
	v_mov_b32_e32 v74, v0
	v_mov_b32_e32 v75, v0
	v_mov_b32_e32 v76, v0
	v_mov_b32_e32 v77, v0
	v_mov_b32_e32 v78, v0
	v_mov_b32_e32 v79, v0
	v_mov_b32_e32 v80, v0
	v_mov_b32_e32 v81, v0
	v_mov_b32_e32 v82, v0
	v_mov_b32_e32 v83, v0
	v_mov_b32_e32 v84, v0
	v_mov_b32_e32 v85, v0
	v_mov_b32_e32 v86, v0
	v_mov_b32_e32 v87, v0
	v_mov_b32_e32 v88, v0
	v_mov_b32_e32 v89, v0
	v_mov_b32_e32 v90, v0
	v_mov_b32_e32 v91, v0
	v_mov_b32_e32 v92, v0
	v_mov_b32_e32 v93, v0
	v_mov_b32_e32 v94, v0
	v_mov_b32_e32 v95, v0
	v_mov_b32_e32 v96, v0
	v_mov_b32_e32 v97, v0
	v_mov_b32_e32 v98, v0
	v_mov_b32_e32 v99, v0
	v_mov_b32_e32 v100, v0
	v_mov_b32_e32 v101, v0
	v_mov_b32_e32 v102, v0
	v_mov_b32_e32 v103, v0
	v_mov_b32_e32 v104, v0
	v_mov_b32_e32 v105, v0
	v_mov_b32_e32 v106, v0
	v_mov_b32_e32 v107, v0
	v_mov_b32_e32 v108, v0
	v_mov_b32_e32 v109, v0
	v_mov_b32_e32 v110, v0
	v_mov_b32_e32 v111, v0
	v_mov_b32_e32 v112, v0
	v_mov_b32_e32 v113, v0
	v_mov_b32_e32 v114, v0
	v_mov_b32_e32 v115, v0
	v_mov_b32_e32 v116, v0
	v_mov_b32_e32 v117, v0
	v_mov_b32_e32 v118, v0
	v_mov_b32_e32 v119, v0
	v_mov_b32_e32 v120, v0
	v_mov_b32_e32 v121, v0
	v_mov_b32_e32 v122, v0
	v_mov_b32_e32 v123, v0
	v_mov_b32_e32 v124, v0
	v_mov_b32_e32 v125, v0
	v_mov_b32_e32 v126, v0
	v_mov_b32_e32 v127, v0
	v_readlane_b32 s16, v254, 36
	v_readlane_b32 s17, v254, 37
	s_nop 0
	s_load_dwordx2 s[54:55], s[16:17], 0x50
	s_waitcnt lgkmcnt(0)
	s_barrier
	s_branch .LBB0_965

; DI void phase_outproj(const Params& p, const GroupP& g, int l, char* smem, int vb) {
;     ...
;         [&](int kt) {
;           int k0 = kt * 64;
;           if (k0 < 512) return ASrc{uf + k0, 512};
;           if (k0 < 1536) { int kk = k0 - 512; return ASrc{q + (kk >> 7) * 192 + (kk & 127), 1536}; }
;           return ASrc{qd + (k0 - 1536), 512};
;         },
.LBB0_965:
	s_add_i32 s9, s41, 1
	s_cmp_gt_u32 s41, 6
	s_mov_b64 s[24:25], -1
	s_cbranch_scc0 .LBB0_971
	s_cmp_gt_u32 s41, 22
	s_mov_b64 s[22:23], -1
	s_cbranch_scc0 .LBB0_968
	s_lshl_b32 s14, s9, 7
	s_mov_b64 s[22:23], 0
	s_add_u32 s14, s54, s14
	s_addc_u32 s15, s55, 0
	s_add_u32 s14, s14, 0xfffff400
	s_addc_u32 s15, s15, -1
